# v91 with the MLP-up epilogue re-emitted with scalar f32 ops only (no packed multiplies), in place, regular schedule
# speedup vs baseline: 1.0104x; 1.0104x over previous
.LBB0_1200:
	v_lshl_add_u32 v147, s5, 10, v142
	ds_read_b32 v150, v147
	ds_read_b32 v152, v147 offset:64
	ds_read_b32 v154, v147 offset:128
	ds_read_b32 v156, v147 offset:192
	ds_read_b32 v158, v147 offset:512
	ds_read_b32 v160, v147 offset:576
	ds_read_b32 v162, v147 offset:640
	ds_read_b32 v164, v147 offset:704
	v_lshl_or_b32 v145, s6, 9, v143
	s_lshl_b32 s5, s7, 21
	v_add3_u32 v145, s5, v141, v145
	s_andn2_b64 vcc, exec, s[40:41]
	s_mov_b64 s[40:41], -1
	s_waitcnt lgkmcnt(0)
	v_mul_f32_e32 v114, v114, v150
	v_mul_f32_e32 v115, v115, v150
	v_mul_f32_e32 v116, v116, v150
	v_mul_f32_e32 v117, v117, v150
	v_mul_f32_e32 v118, v118, v150
	v_mul_f32_e32 v119, v119, v150
	v_mul_f32_e32 v120, v120, v150
	v_mul_f32_e32 v121, v121, v150
	v_mul_f32_e32 v122, v122, v150
	v_mul_f32_e32 v123, v123, v150
	v_mul_f32_e32 v124, v124, v150
	v_mul_f32_e32 v125, v125, v150
	v_mul_f32_e32 v126, v126, v150
	v_mul_f32_e32 v127, v127, v150
	v_mul_f32_e32 v128, v128, v150
	v_mul_f32_e32 v129, v129, v150
	v_max_f32_e32 v114, 0, v114
	v_max_f32_e32 v115, 0, v115
	v_max_f32_e32 v116, 0, v116
	v_max_f32_e32 v117, 0, v117
	v_max_f32_e32 v118, 0, v118
	v_max_f32_e32 v119, 0, v119
	v_max_f32_e32 v120, 0, v120
	v_max_f32_e32 v121, 0, v121
	v_max_f32_e32 v122, 0, v122
	v_max_f32_e32 v123, 0, v123
	v_max_f32_e32 v124, 0, v124
	v_max_f32_e32 v125, 0, v125
	v_max_f32_e32 v126, 0, v126
	v_max_f32_e32 v127, 0, v127
	v_max_f32_e32 v128, 0, v128
	v_max_f32_e32 v129, 0, v129
	v_mul_f32_e32 v114, v114, v114
	v_mul_f32_e32 v115, v115, v115
	v_mul_f32_e32 v116, v116, v116
	v_mul_f32_e32 v117, v117, v117
	v_mul_f32_e32 v118, v118, v118
	v_mul_f32_e32 v119, v119, v119
	v_mul_f32_e32 v120, v120, v120
	v_mul_f32_e32 v121, v121, v121
	v_mul_f32_e32 v122, v122, v122
	v_mul_f32_e32 v123, v123, v123
	v_mul_f32_e32 v124, v124, v124
	v_mul_f32_e32 v125, v125, v125
	v_mul_f32_e32 v126, v126, v126
	v_mul_f32_e32 v127, v127, v127
	v_mul_f32_e32 v128, v128, v128
	v_mul_f32_e32 v129, v129, v129
	v_or_b32_e32 v183, 0x100, v145
	v_cvt_pk_bf16_f32 v166, v126, v127
	v_cvt_pk_bf16_f32 v167, v128, v129
	v_cvt_pk_bf16_f32 v168, v122, v123
	v_cvt_pk_bf16_f32 v169, v124, v125
	global_store_dwordx4 v145, v[166:169], s[42:43]
	v_cvt_pk_bf16_f32 v170, v118, v119
	v_cvt_pk_bf16_f32 v171, v120, v121
	v_cvt_pk_bf16_f32 v172, v114, v115
	v_cvt_pk_bf16_f32 v173, v116, v117
	global_store_dwordx4 v183, v[170:173], s[42:43]
	v_mul_f32_e32 v98, v98, v152
	v_mul_f32_e32 v99, v99, v152
	v_mul_f32_e32 v100, v100, v152
	v_mul_f32_e32 v101, v101, v152
	v_mul_f32_e32 v102, v102, v152
	v_mul_f32_e32 v103, v103, v152
	v_mul_f32_e32 v104, v104, v152
	v_mul_f32_e32 v105, v105, v152
	v_mul_f32_e32 v106, v106, v152
	v_mul_f32_e32 v107, v107, v152
	v_mul_f32_e32 v108, v108, v152
	v_mul_f32_e32 v109, v109, v152
	v_mul_f32_e32 v110, v110, v152
	v_mul_f32_e32 v111, v111, v152
	v_mul_f32_e32 v112, v112, v152
	v_mul_f32_e32 v113, v113, v152
	v_max_f32_e32 v98, 0, v98
	v_max_f32_e32 v99, 0, v99
	v_max_f32_e32 v100, 0, v100
	v_max_f32_e32 v101, 0, v101
	v_max_f32_e32 v102, 0, v102
	v_max_f32_e32 v103, 0, v103
	v_max_f32_e32 v104, 0, v104
	v_max_f32_e32 v105, 0, v105
	v_max_f32_e32 v106, 0, v106
	v_max_f32_e32 v107, 0, v107
	v_max_f32_e32 v108, 0, v108
	v_max_f32_e32 v109, 0, v109
	v_max_f32_e32 v110, 0, v110
	v_max_f32_e32 v111, 0, v111
	v_max_f32_e32 v112, 0, v112
	v_max_f32_e32 v113, 0, v113
	v_mul_f32_e32 v98, v98, v98
	v_mul_f32_e32 v99, v99, v99
	v_mul_f32_e32 v100, v100, v100
	v_mul_f32_e32 v101, v101, v101
	v_mul_f32_e32 v102, v102, v102
	v_mul_f32_e32 v103, v103, v103
	v_mul_f32_e32 v104, v104, v104
	v_mul_f32_e32 v105, v105, v105
	v_mul_f32_e32 v106, v106, v106
	v_mul_f32_e32 v107, v107, v107
	v_mul_f32_e32 v108, v108, v108
	v_mul_f32_e32 v109, v109, v109
	v_mul_f32_e32 v110, v110, v110
	v_mul_f32_e32 v111, v111, v111
	v_mul_f32_e32 v112, v112, v112
	v_mul_f32_e32 v113, v113, v113
	v_add_u32_e32 v184, 0x20000, v145
	v_add_u32_e32 v185, 0x20100, v145
	v_cvt_pk_bf16_f32 v174, v110, v111
	v_cvt_pk_bf16_f32 v175, v112, v113
	v_cvt_pk_bf16_f32 v176, v106, v107
	v_cvt_pk_bf16_f32 v177, v108, v109
	global_store_dwordx4 v184, v[174:177], s[42:43]
	v_cvt_pk_bf16_f32 v178, v102, v103
	v_cvt_pk_bf16_f32 v179, v104, v105
	v_cvt_pk_bf16_f32 v180, v98, v99
	v_cvt_pk_bf16_f32 v181, v100, v101
	global_store_dwordx4 v185, v[178:181], s[42:43]
	v_mul_f32_e32 v82, v82, v154
	v_mul_f32_e32 v83, v83, v154
	v_mul_f32_e32 v84, v84, v154
	v_mul_f32_e32 v85, v85, v154
	v_mul_f32_e32 v86, v86, v154
	v_mul_f32_e32 v87, v87, v154
	v_mul_f32_e32 v88, v88, v154
	v_mul_f32_e32 v89, v89, v154
	v_mul_f32_e32 v90, v90, v154
	v_mul_f32_e32 v91, v91, v154
	v_mul_f32_e32 v92, v92, v154
	v_mul_f32_e32 v93, v93, v154
	v_mul_f32_e32 v94, v94, v154
	v_mul_f32_e32 v95, v95, v154
	v_mul_f32_e32 v96, v96, v154
	v_mul_f32_e32 v97, v97, v154
	v_max_f32_e32 v82, 0, v82
	v_max_f32_e32 v83, 0, v83
	v_max_f32_e32 v84, 0, v84
	v_max_f32_e32 v85, 0, v85
	v_max_f32_e32 v86, 0, v86
	v_max_f32_e32 v87, 0, v87
	v_max_f32_e32 v88, 0, v88
	v_max_f32_e32 v89, 0, v89
	v_max_f32_e32 v90, 0, v90
	v_max_f32_e32 v91, 0, v91
	v_max_f32_e32 v92, 0, v92
	v_max_f32_e32 v93, 0, v93
	v_max_f32_e32 v94, 0, v94
	v_max_f32_e32 v95, 0, v95
	v_max_f32_e32 v96, 0, v96
	v_max_f32_e32 v97, 0, v97
	v_mul_f32_e32 v82, v82, v82
	v_mul_f32_e32 v83, v83, v83
	v_mul_f32_e32 v84, v84, v84
	v_mul_f32_e32 v85, v85, v85
	v_mul_f32_e32 v86, v86, v86
	v_mul_f32_e32 v87, v87, v87
	v_mul_f32_e32 v88, v88, v88
	v_mul_f32_e32 v89, v89, v89
	v_mul_f32_e32 v90, v90, v90
	v_mul_f32_e32 v91, v91, v91
	v_mul_f32_e32 v92, v92, v92
	v_mul_f32_e32 v93, v93, v93
	v_mul_f32_e32 v94, v94, v94
	v_mul_f32_e32 v95, v95, v95
	v_mul_f32_e32 v96, v96, v96
	v_mul_f32_e32 v97, v97, v97
	v_add_u32_e32 v182, 0x40000, v145
	v_add_u32_e32 v183, 0x40100, v145
	v_cvt_pk_bf16_f32 v166, v94, v95
	v_cvt_pk_bf16_f32 v167, v96, v97
	v_cvt_pk_bf16_f32 v168, v90, v91
	v_cvt_pk_bf16_f32 v169, v92, v93
	global_store_dwordx4 v182, v[166:169], s[42:43]
	v_cvt_pk_bf16_f32 v170, v86, v87
	v_cvt_pk_bf16_f32 v171, v88, v89
	v_cvt_pk_bf16_f32 v172, v82, v83
	v_cvt_pk_bf16_f32 v173, v84, v85
	global_store_dwordx4 v183, v[170:173], s[42:43]
	v_mul_f32_e32 v66, v66, v156
	v_mul_f32_e32 v67, v67, v156
	v_mul_f32_e32 v68, v68, v156
	v_mul_f32_e32 v69, v69, v156
	v_mul_f32_e32 v70, v70, v156
	v_mul_f32_e32 v71, v71, v156
	v_mul_f32_e32 v72, v72, v156
	v_mul_f32_e32 v73, v73, v156
	v_mul_f32_e32 v74, v74, v156
	v_mul_f32_e32 v75, v75, v156
	v_mul_f32_e32 v76, v76, v156
	v_mul_f32_e32 v77, v77, v156
	v_mul_f32_e32 v78, v78, v156
	v_mul_f32_e32 v79, v79, v156
	v_mul_f32_e32 v80, v80, v156
	v_mul_f32_e32 v81, v81, v156
	v_max_f32_e32 v66, 0, v66
	v_max_f32_e32 v67, 0, v67
	v_max_f32_e32 v68, 0, v68
	v_max_f32_e32 v69, 0, v69
	v_max_f32_e32 v70, 0, v70
	v_max_f32_e32 v71, 0, v71
	v_max_f32_e32 v72, 0, v72
	v_max_f32_e32 v73, 0, v73
	v_max_f32_e32 v74, 0, v74
	v_max_f32_e32 v75, 0, v75
	v_max_f32_e32 v76, 0, v76
	v_max_f32_e32 v77, 0, v77
	v_max_f32_e32 v78, 0, v78
	v_max_f32_e32 v79, 0, v79
	v_max_f32_e32 v80, 0, v80
	v_max_f32_e32 v81, 0, v81
	v_mul_f32_e32 v66, v66, v66
	v_mul_f32_e32 v67, v67, v67
	v_mul_f32_e32 v68, v68, v68
	v_mul_f32_e32 v69, v69, v69
	v_mul_f32_e32 v70, v70, v70
	v_mul_f32_e32 v71, v71, v71
	v_mul_f32_e32 v72, v72, v72
	v_mul_f32_e32 v73, v73, v73
	v_mul_f32_e32 v74, v74, v74
	v_mul_f32_e32 v75, v75, v75
	v_mul_f32_e32 v76, v76, v76
	v_mul_f32_e32 v77, v77, v77
	v_mul_f32_e32 v78, v78, v78
	v_mul_f32_e32 v79, v79, v79
	v_mul_f32_e32 v80, v80, v80
	v_mul_f32_e32 v81, v81, v81
	v_add_u32_e32 v184, 0x60000, v145
	v_add_u32_e32 v185, 0x60100, v145
	v_cvt_pk_bf16_f32 v174, v78, v79
	v_cvt_pk_bf16_f32 v175, v80, v81
	v_cvt_pk_bf16_f32 v176, v74, v75
	v_cvt_pk_bf16_f32 v177, v76, v77
	global_store_dwordx4 v184, v[174:177], s[42:43]
	v_cvt_pk_bf16_f32 v178, v70, v71
	v_cvt_pk_bf16_f32 v179, v72, v73
	v_cvt_pk_bf16_f32 v180, v66, v67
	v_cvt_pk_bf16_f32 v181, v68, v69
	global_store_dwordx4 v185, v[178:181], s[42:43]
	v_mul_f32_e32 v50, v50, v158
	v_mul_f32_e32 v51, v51, v158
	v_mul_f32_e32 v52, v52, v158
	v_mul_f32_e32 v53, v53, v158
	v_mul_f32_e32 v54, v54, v158
	v_mul_f32_e32 v55, v55, v158
	v_mul_f32_e32 v56, v56, v158
	v_mul_f32_e32 v57, v57, v158
	v_mul_f32_e32 v58, v58, v158
	v_mul_f32_e32 v59, v59, v158
	v_mul_f32_e32 v60, v60, v158
	v_mul_f32_e32 v61, v61, v158
	v_mul_f32_e32 v62, v62, v158
	v_mul_f32_e32 v63, v63, v158
	v_mul_f32_e32 v64, v64, v158
	v_mul_f32_e32 v65, v65, v158
	v_max_f32_e32 v50, 0, v50
	v_max_f32_e32 v51, 0, v51
	v_max_f32_e32 v52, 0, v52
	v_max_f32_e32 v53, 0, v53
	v_max_f32_e32 v54, 0, v54
	v_max_f32_e32 v55, 0, v55
	v_max_f32_e32 v56, 0, v56
	v_max_f32_e32 v57, 0, v57
	v_max_f32_e32 v58, 0, v58
	v_max_f32_e32 v59, 0, v59
	v_max_f32_e32 v60, 0, v60
	v_max_f32_e32 v61, 0, v61
	v_max_f32_e32 v62, 0, v62
	v_max_f32_e32 v63, 0, v63
	v_max_f32_e32 v64, 0, v64
	v_max_f32_e32 v65, 0, v65
	v_mul_f32_e32 v50, v50, v50
	v_mul_f32_e32 v51, v51, v51
	v_mul_f32_e32 v52, v52, v52
	v_mul_f32_e32 v53, v53, v53
	v_mul_f32_e32 v54, v54, v54
	v_mul_f32_e32 v55, v55, v55
	v_mul_f32_e32 v56, v56, v56
	v_mul_f32_e32 v57, v57, v57
	v_mul_f32_e32 v58, v58, v58
	v_mul_f32_e32 v59, v59, v59
	v_mul_f32_e32 v60, v60, v60
	v_mul_f32_e32 v61, v61, v61
	v_mul_f32_e32 v62, v62, v62
	v_mul_f32_e32 v63, v63, v63
	v_mul_f32_e32 v64, v64, v64
	v_mul_f32_e32 v65, v65, v65
	v_add_u32_e32 v182, 0x100000, v145
	v_add_u32_e32 v183, 0x100100, v145
	v_cvt_pk_bf16_f32 v166, v62, v63
	v_cvt_pk_bf16_f32 v167, v64, v65
	v_cvt_pk_bf16_f32 v168, v58, v59
	v_cvt_pk_bf16_f32 v169, v60, v61
	global_store_dwordx4 v182, v[166:169], s[42:43]
	v_cvt_pk_bf16_f32 v170, v54, v55
	v_cvt_pk_bf16_f32 v171, v56, v57
	v_cvt_pk_bf16_f32 v172, v50, v51
	v_cvt_pk_bf16_f32 v173, v52, v53
	global_store_dwordx4 v183, v[170:173], s[42:43]
	v_mul_f32_e32 v34, v34, v160
	v_mul_f32_e32 v35, v35, v160
	v_mul_f32_e32 v36, v36, v160
	v_mul_f32_e32 v37, v37, v160
	v_mul_f32_e32 v38, v38, v160
	v_mul_f32_e32 v39, v39, v160
	v_mul_f32_e32 v40, v40, v160
	v_mul_f32_e32 v41, v41, v160
	v_mul_f32_e32 v42, v42, v160
	v_mul_f32_e32 v43, v43, v160
	v_mul_f32_e32 v44, v44, v160
	v_mul_f32_e32 v45, v45, v160
	v_mul_f32_e32 v46, v46, v160
	v_mul_f32_e32 v47, v47, v160
	v_mul_f32_e32 v48, v48, v160
	v_mul_f32_e32 v49, v49, v160
	v_max_f32_e32 v34, 0, v34
	v_max_f32_e32 v35, 0, v35
	v_max_f32_e32 v36, 0, v36
	v_max_f32_e32 v37, 0, v37
	v_max_f32_e32 v38, 0, v38
	v_max_f32_e32 v39, 0, v39
	v_max_f32_e32 v40, 0, v40
	v_max_f32_e32 v41, 0, v41
	v_max_f32_e32 v42, 0, v42
	v_max_f32_e32 v43, 0, v43
	v_max_f32_e32 v44, 0, v44
	v_max_f32_e32 v45, 0, v45
	v_max_f32_e32 v46, 0, v46
	v_max_f32_e32 v47, 0, v47
	v_max_f32_e32 v48, 0, v48
	v_max_f32_e32 v49, 0, v49
	v_mul_f32_e32 v34, v34, v34
	v_mul_f32_e32 v35, v35, v35
	v_mul_f32_e32 v36, v36, v36
	v_mul_f32_e32 v37, v37, v37
	v_mul_f32_e32 v38, v38, v38
	v_mul_f32_e32 v39, v39, v39
	v_mul_f32_e32 v40, v40, v40
	v_mul_f32_e32 v41, v41, v41
	v_mul_f32_e32 v42, v42, v42
	v_mul_f32_e32 v43, v43, v43
	v_mul_f32_e32 v44, v44, v44
	v_mul_f32_e32 v45, v45, v45
	v_mul_f32_e32 v46, v46, v46
	v_mul_f32_e32 v47, v47, v47
	v_mul_f32_e32 v48, v48, v48
	v_mul_f32_e32 v49, v49, v49
	v_add_u32_e32 v184, 0x120000, v145
	v_add_u32_e32 v185, 0x120100, v145
	v_cvt_pk_bf16_f32 v174, v46, v47
	v_cvt_pk_bf16_f32 v175, v48, v49
	v_cvt_pk_bf16_f32 v176, v42, v43
	v_cvt_pk_bf16_f32 v177, v44, v45
	global_store_dwordx4 v184, v[174:177], s[42:43]
	v_cvt_pk_bf16_f32 v178, v38, v39
	v_cvt_pk_bf16_f32 v179, v40, v41
	v_cvt_pk_bf16_f32 v180, v34, v35
	v_cvt_pk_bf16_f32 v181, v36, v37
	global_store_dwordx4 v185, v[178:181], s[42:43]
	v_mul_f32_e32 v16, v16, v162
	v_mul_f32_e32 v17, v17, v162
	v_mul_f32_e32 v18, v18, v162
	v_mul_f32_e32 v19, v19, v162
	v_mul_f32_e32 v20, v20, v162
	v_mul_f32_e32 v21, v21, v162
	v_mul_f32_e32 v22, v22, v162
	v_mul_f32_e32 v23, v23, v162
	v_mul_f32_e32 v24, v24, v162
	v_mul_f32_e32 v25, v25, v162
	v_mul_f32_e32 v26, v26, v162
	v_mul_f32_e32 v27, v27, v162
	v_mul_f32_e32 v28, v28, v162
	v_mul_f32_e32 v29, v29, v162
	v_mul_f32_e32 v30, v30, v162
	v_mul_f32_e32 v31, v31, v162
	v_max_f32_e32 v16, 0, v16
	v_max_f32_e32 v17, 0, v17
	v_max_f32_e32 v18, 0, v18
	v_max_f32_e32 v19, 0, v19
	v_max_f32_e32 v20, 0, v20
	v_max_f32_e32 v21, 0, v21
	v_max_f32_e32 v22, 0, v22
	v_max_f32_e32 v23, 0, v23
	v_max_f32_e32 v24, 0, v24
	v_max_f32_e32 v25, 0, v25
	v_max_f32_e32 v26, 0, v26
	v_max_f32_e32 v27, 0, v27
	v_max_f32_e32 v28, 0, v28
	v_max_f32_e32 v29, 0, v29
	v_max_f32_e32 v30, 0, v30
	v_max_f32_e32 v31, 0, v31
	v_mul_f32_e32 v16, v16, v16
	v_mul_f32_e32 v17, v17, v17
	v_mul_f32_e32 v18, v18, v18
	v_mul_f32_e32 v19, v19, v19
	v_mul_f32_e32 v20, v20, v20
	v_mul_f32_e32 v21, v21, v21
	v_mul_f32_e32 v22, v22, v22
	v_mul_f32_e32 v23, v23, v23
	v_mul_f32_e32 v24, v24, v24
	v_mul_f32_e32 v25, v25, v25
	v_mul_f32_e32 v26, v26, v26
	v_mul_f32_e32 v27, v27, v27
	v_mul_f32_e32 v28, v28, v28
	v_mul_f32_e32 v29, v29, v29
	v_mul_f32_e32 v30, v30, v30
	v_mul_f32_e32 v31, v31, v31
	v_add_u32_e32 v182, 0x140000, v145
	v_add_u32_e32 v183, 0x140100, v145
	v_cvt_pk_bf16_f32 v166, v28, v29
	v_cvt_pk_bf16_f32 v167, v30, v31
	v_cvt_pk_bf16_f32 v168, v24, v25
	v_cvt_pk_bf16_f32 v169, v26, v27
	global_store_dwordx4 v182, v[166:169], s[42:43]
	v_cvt_pk_bf16_f32 v170, v20, v21
	v_cvt_pk_bf16_f32 v171, v22, v23
	v_cvt_pk_bf16_f32 v172, v16, v17
	v_cvt_pk_bf16_f32 v173, v18, v19
	global_store_dwordx4 v183, v[170:173], s[42:43]
	v_mul_f32_e32 v0, v0, v164
	v_mul_f32_e32 v1, v1, v164
	v_mul_f32_e32 v2, v2, v164
	v_mul_f32_e32 v3, v3, v164
	v_mul_f32_e32 v4, v4, v164
	v_mul_f32_e32 v5, v5, v164
	v_mul_f32_e32 v6, v6, v164
	v_mul_f32_e32 v7, v7, v164
	v_mul_f32_e32 v8, v8, v164
	v_mul_f32_e32 v9, v9, v164
	v_mul_f32_e32 v10, v10, v164
	v_mul_f32_e32 v11, v11, v164
	v_mul_f32_e32 v12, v12, v164
	v_mul_f32_e32 v13, v13, v164
	v_mul_f32_e32 v14, v14, v164
	v_mul_f32_e32 v15, v15, v164
	v_max_f32_e32 v0, 0, v0
	v_max_f32_e32 v1, 0, v1
	v_max_f32_e32 v2, 0, v2
	v_max_f32_e32 v3, 0, v3
	v_max_f32_e32 v4, 0, v4
	v_max_f32_e32 v5, 0, v5
	v_max_f32_e32 v6, 0, v6
	v_max_f32_e32 v7, 0, v7
	v_max_f32_e32 v8, 0, v8
	v_max_f32_e32 v9, 0, v9
	v_max_f32_e32 v10, 0, v10
	v_max_f32_e32 v11, 0, v11
	v_max_f32_e32 v12, 0, v12
	v_max_f32_e32 v13, 0, v13
	v_max_f32_e32 v14, 0, v14
	v_max_f32_e32 v15, 0, v15
	v_mul_f32_e32 v0, v0, v0
	v_mul_f32_e32 v1, v1, v1
	v_mul_f32_e32 v2, v2, v2
	v_mul_f32_e32 v3, v3, v3
	v_mul_f32_e32 v4, v4, v4
	v_mul_f32_e32 v5, v5, v5
	v_mul_f32_e32 v6, v6, v6
	v_mul_f32_e32 v7, v7, v7
	v_mul_f32_e32 v8, v8, v8
	v_mul_f32_e32 v9, v9, v9
	v_mul_f32_e32 v10, v10, v10
	v_mul_f32_e32 v11, v11, v11
	v_mul_f32_e32 v12, v12, v12
	v_mul_f32_e32 v13, v13, v13
	v_mul_f32_e32 v14, v14, v14
	v_mul_f32_e32 v15, v15, v15
	v_add_u32_e32 v184, 0x160000, v145
	v_add_u32_e32 v185, 0x160100, v145
	v_cvt_pk_bf16_f32 v174, v12, v13
	v_cvt_pk_bf16_f32 v175, v14, v15
	v_cvt_pk_bf16_f32 v176, v8, v9
	v_cvt_pk_bf16_f32 v177, v10, v11
	global_store_dwordx4 v184, v[174:177], s[42:43]
	v_cvt_pk_bf16_f32 v178, v4, v5
	v_cvt_pk_bf16_f32 v179, v6, v7
	v_cvt_pk_bf16_f32 v180, v0, v1
	v_cvt_pk_bf16_f32 v181, v2, v3
	global_store_dwordx4 v185, v[178:181], s[42:43]
	s_cbranch_vccnz .LBB0_1189
	s_andn2_b64 vcc, exec, s[0:1]
	s_cbranch_vccnz .LBB0_1188
	s_barrier
	s_branch .LBB0_1188
